# P3 v12: v6 + first two LDS-DMA stages issued before the per-thread address setup (prologue de-serialisation of the scan start-up)
# baseline (speedup 1.0000x reference)
; #define LAS __attribute__((address_space(3)))
; __device__ __forceinline__ void gla_scan_item(const Ctx& C, int item, LAS unsigned char* lds, int tid) {
;     const int jx = item >> 3, bh = (item & 7) * 4 + (jx >> 3), sl = jx & 7, b = bh >> 2, h = bh & 3;
;     LAS bf16* Aq = (LAS bf16*)lds;
;     LAS bf16* Bc = (LAS bf16*)(lds + 25600);
;     LAS bf16* Kt = (LAS bf16*)(lds + 38400);
;     const int wave = tid >> 6, lane = tid & 63, l15 = lane & 15, quad = lane >> 4;
;     f32x4 S[2] = {(f32x4){0.f, 0.f, 0.f, 0.f}, (f32x4){0.f, 0.f, 0.f, 0.f}};
;     *(LAS u32x4*)(Bc + (tid >> 4) * 200 + (tid & 15) * 8) = (u32x4){0u, 0u, 0u, 0u};
;     u32x4 rq0A, rq1A, rsA, rk0A, rk1A, rvA = (u32x4){0u, 0u, 0u, 0u}; f32x4 rdA;
;     u32x4 rq0B, rq1B, rsB, rk0B, rk1B, rvB = (u32x4){0u, 0u, 0u, 0u}; f32x4 rdB;
.LBB0_428:
	s_cmp_lt_i32 s96, 4
	s_cselect_b64 s[4:5], -1, 0
	s_add_u32 s6, s94, 0xb300000
	s_addc_u32 s7, s95, 0
	s_and_b64 s[0:1], s[4:5], s[0:1]
	s_andn2_b64 vcc, exec, s[0:1]
	s_cbranch_vccnz .LBB0_496
	s_cmpk_gt_i32 s2, 0xff
	s_cbranch_scc1 .LBB0_496
	v_readfirstlane_b32 s32, v163
	v_and_b32_e32 v203, 63, v162
	v_and_b32_e32 v202, 15, v162
	v_bfe_u32 v201, v162, 4, 2
	v_lshrrev_b32_e32 v200, 4, v203
	v_lshl_add_u32 v200, v163, 3, v200
	v_and_b32_e32 v199, 15, v200
	v_xor_b32_e32 v199, v199, v202
	v_lshlrev_b32_e32 v255, 10, v200
	v_lshl_add_u32 v255, v199, 4, v255
	v_lshrrev_b32_e32 v200, 4, v203
	v_lshl_add_u32 v200, v163, 3, v200
	v_add_u32_e32 v200, 4, v200
	v_and_b32_e32 v199, 15, v200
	v_xor_b32_e32 v199, v199, v202
	v_lshlrev_b32_e32 v254, 10, v200
	v_lshl_add_u32 v254, v199, 4, v254
	v_lshrrev_b32_e32 v200, 3, v203
	v_lshl_add_u32 v200, v163, 3, v200
	v_bfe_u32 v199, v200, 1, 3
	v_and_b32_e32 v198, 7, v203
	v_xor_b32_e32 v199, v199, v198
	v_lshlrev_b32_e32 v253, 7, v200
	v_lshl_add_u32 v253, v199, 4, v253
	v_lshrrev_b32_e32 v200, 3, v203
	v_lshl_add_u32 v200, v163, 4, v200
	v_bfe_u32 v199, v200, 1, 3
	v_and_b32_e32 v198, 7, v203
	v_xor_b32_e32 v199, v199, v198
	v_lshlrev_b32_e32 v252, 7, v200
	v_lshl_add_u32 v252, v199, 4, v252
	v_lshrrev_b32_e32 v200, 3, v203
	v_lshl_add_u32 v200, v163, 4, v200
	v_add_u32_e32 v200, 8, v200
	v_bfe_u32 v199, v200, 1, 3
	v_and_b32_e32 v198, 7, v203
	v_xor_b32_e32 v199, v199, v198
	v_lshlrev_b32_e32 v251, 7, v200
	v_lshl_add_u32 v251, v199, 4, v251
	s_lshl_b32 s46, s32, 11
	s_lshl_b32 s47, s32, 10
	s_add_i32 s47, s47, 0x4000
	s_add_i32 s48, s46, 0x6000
	s_mov_b32 s3, s2
	s_lshr_b32 s4, s3, 3
	s_and_b32 s41, s4, 7
	s_lshr_b32 s5, s4, 3
	s_and_b32 s37, s3, 7
	s_lshl_b32 s37, s37, 2
	s_add_i32 s37, s37, s5
	s_lshr_b32 s39, s37, 2
	s_and_b32 s40, s37, 3
	s_add_u32 s8, s94, 0x1d800000
	s_addc_u32 s9, s95, 0
	s_lshl_b32 s31, s39, 21
	s_add_u32 s8, s8, s31
	s_addc_u32 s9, s9, 0
	s_lshl_b32 s31, s40, 8
	s_add_u32 s8, s8, s31
	s_addc_u32 s9, s9, 0
	s_add_u32 s10, s94, 0x2f00000
	s_addc_u32 s11, s95, 0
	s_lshl_b32 s31, s37, 18
	s_add_u32 s10, s10, s31
	s_addc_u32 s11, s11, 0
	s_add_u32 s12, s94, 0x3700000
	s_addc_u32 s13, s95, 0
	s_lshl_b32 s31, s37, 19
	s_add_u32 s12, s12, s31
	s_addc_u32 s13, s13, 0
	s_mov_b32 m0, s46
	s_nop 0
	global_load_lds_dwordx4 v255, s[8:9]
	s_add_i32 m0, s46, 0x400
	s_nop 0
	global_load_lds_dwordx4 v254, s[8:9]
	s_mov_b32 m0, s47
	s_nop 0
	global_load_lds_dwordx4 v253, s[10:11]
	s_mov_b32 m0, s48
	s_nop 0
	global_load_lds_dwordx4 v252, s[12:13]
	s_add_i32 m0, s48, 0x400
	s_nop 0
	global_load_lds_dwordx4 v251, s[12:13]
	s_add_u32 s8, s8, 0x10000
	s_addc_u32 s9, s9, 0
	s_add_u32 s10, s10, 0x2000
	s_addc_u32 s11, s11, 0
	s_add_u32 s12, s12, 0x4000
	s_addc_u32 s13, s13, 0
	s_add_i32 m0, s46, 0xa000
	s_nop 0
	global_load_lds_dwordx4 v255, s[8:9]
	s_add_i32 m0, s46, 0xa400
	s_nop 0
	global_load_lds_dwordx4 v254, s[8:9]
	s_add_i32 m0, s47, 0xa000
	s_nop 0
	global_load_lds_dwordx4 v253, s[10:11]
	s_add_i32 m0, s48, 0xa000
	s_nop 0
	global_load_lds_dwordx4 v252, s[12:13]
	s_add_i32 m0, s48, 0xa400
	s_nop 0
	global_load_lds_dwordx4 v251, s[12:13]
	s_add_u32 s8, s8, 0x10000
	s_addc_u32 s9, s9, 0
	s_add_u32 s10, s10, 0x2000
	s_addc_u32 s11, s11, 0
	s_add_u32 s12, s12, 0x4000
	s_addc_u32 s13, s13, 0
	s_mov_b32 s49, 1
	v_and_b32_e32 v200, 1, v163
	v_lshl_add_u32 v200, v200, 5, v202
	v_or_b32_e32 v199, 0, v201
	v_and_b32_e32 v198, 15, v200
	v_xor_b32_e32 v199, v199, v198
	v_lshlrev_b32_e32 v241, 8, v200
	v_lshl_add_u32 v241, v199, 4, v241
	v_or_b32_e32 v199, 4, v201
	v_and_b32_e32 v198, 15, v200
	v_xor_b32_e32 v199, v199, v198
	v_lshlrev_b32_e32 v240, 8, v200
	v_lshl_add_u32 v240, v199, 4, v240
	v_or_b32_e32 v199, 8, v201
	v_and_b32_e32 v198, 15, v200
	v_xor_b32_e32 v199, v199, v198
	v_lshlrev_b32_e32 v239, 8, v200
	v_lshl_add_u32 v239, v199, 4, v239
	v_or_b32_e32 v199, 12, v201
	v_and_b32_e32 v198, 15, v200
	v_xor_b32_e32 v199, v199, v198
	v_lshlrev_b32_e32 v238, 8, v200
	v_lshl_add_u32 v238, v199, 4, v238
	v_or_b32_e32 v199, 0, v201
	v_bfe_u32 v198, v200, 1, 3
	v_xor_b32_e32 v199, v199, v198
	v_lshlrev_b32_e32 v231, 7, v200
	v_lshl_add_u32 v231, v199, 4, v231
	v_add_u32_e32 v231, 0x4000, v231
	v_or_b32_e32 v199, 4, v201
	v_bfe_u32 v198, v200, 1, 3
	v_xor_b32_e32 v199, v199, v198
	v_lshlrev_b32_e32 v230, 7, v200
	v_lshl_add_u32 v230, v199, 4, v230
	v_add_u32_e32 v230, 0x4000, v230
	v_lshlrev_b32_e32 v248, 11, v200
	v_lshl_add_u32 v248, v201, 3, v248
	v_add_u32_e32 v247, 0x8000, v248
	v_or_b32_e32 v199, 0, v201
	v_and_b32_e32 v198, 15, v202
	v_xor_b32_e32 v199, v199, v198
	v_lshlrev_b32_e32 v223, 8, v202
	v_lshl_add_u32 v223, v199, 4, v223
	v_add_u32_e32 v223, 0x1e000, v223
	v_or_b32_e32 v199, 4, v201
	v_and_b32_e32 v198, 15, v202
	v_xor_b32_e32 v199, v199, v198
	v_lshlrev_b32_e32 v222, 8, v202
	v_lshl_add_u32 v222, v199, 4, v222
	v_add_u32_e32 v222, 0x1e000, v222
	v_or_b32_e32 v199, 8, v201
	v_and_b32_e32 v198, 15, v202
	v_xor_b32_e32 v199, v199, v198
	v_lshlrev_b32_e32 v221, 8, v202
	v_lshl_add_u32 v221, v199, 4, v221
	v_add_u32_e32 v221, 0x1e000, v221
	v_or_b32_e32 v199, 12, v201
	v_and_b32_e32 v198, 15, v202
	v_xor_b32_e32 v199, v199, v198
	v_lshlrev_b32_e32 v220, 8, v202
	v_lshl_add_u32 v220, v199, 4, v220
	v_add_u32_e32 v220, 0x1e000, v220
	v_or_b32_e32 v199, 0, v201
	v_bfe_u32 v198, v202, 1, 3
	v_xor_b32_e32 v199, v199, v198
	v_lshlrev_b32_e32 v219, 7, v202
	v_lshl_add_u32 v219, v199, 4, v219
	v_add_u32_e32 v219, 0x20100, v219
	v_or_b32_e32 v199, 4, v201
	v_bfe_u32 v198, v202, 1, 3
	v_xor_b32_e32 v199, v199, v198
	v_lshlrev_b32_e32 v218, 7, v202
	v_lshl_add_u32 v218, v199, 4, v218
	v_add_u32_e32 v218, 0x20100, v218
	v_and_b32_e32 v200, 1, v163
	v_lshl_add_u32 v200, v200, 6, v202
	v_or_b32_e32 v199, 0, v201
	v_bfe_u32 v198, v200, 1, 3
	v_xor_b32_e32 v199, v199, v198
	v_lshlrev_b32_e32 v227, 7, v200
	v_lshl_add_u32 v227, v199, 4, v227
	v_add_u32_e32 v227, 0x6000, v227
	v_or_b32_e32 v199, 4, v201
	v_bfe_u32 v198, v200, 1, 3
	v_xor_b32_e32 v199, v199, v198
	v_lshlrev_b32_e32 v226, 7, v200
	v_lshl_add_u32 v226, v199, 4, v226
	v_add_u32_e32 v226, 0x6000, v226
	v_or_b32_e32 v199, 0, v201
	v_bfe_u32 v198, v202, 1, 3
	v_xor_b32_e32 v199, v199, v198
	v_lshlrev_b32_e32 v217, 7, v202
	v_lshl_add_u32 v217, v199, 4, v217
	v_add_u32_e32 v217, 0x20100, v217
	v_or_b32_e32 v199, 4, v201
	v_bfe_u32 v198, v202, 1, 3
	v_xor_b32_e32 v199, v199, v198
	v_lshlrev_b32_e32 v216, 7, v202
	v_lshl_add_u32 v216, v199, 4, v216
	v_add_u32_e32 v216, 0x20100, v216
	v_add_u32_e32 v235, 0x14000, v241
	v_add_u32_e32 v234, 0x14000, v240
	v_add_u32_e32 v233, 0x14000, v239
	v_add_u32_e32 v232, 0x14000, v238
	v_add_u32_e32 v229, 0x14000, v231
	v_add_u32_e32 v228, 0x14000, v230
	v_add_u32_e32 v225, 0x14000, v227
	v_add_u32_e32 v224, 0x14000, v226
	v_and_b32_e32 v200, 1, v163
	v_lshrrev_b32_e32 v199, 1, v201
	v_lshl_add_u32 v199, v200, 3, v199
	v_xor_b32_e32 v199, v199, v202
	v_lshlrev_b32_e32 v215, 8, v202
	v_lshl_add_u32 v215, v199, 4, v215
	v_and_b32_e32 v199, 1, v201
	v_lshl_add_u32 v215, v199, 3, v215
	v_add_u32_e32 v215, 0x1e000, v215
	v_and_b32_e32 v200, 1, v163
	v_lshrrev_b32_e32 v199, 1, v201
	v_lshl_add_u32 v199, v200, 3, v199
	v_add_u32_e32 v199, 2, v199
	v_xor_b32_e32 v199, v199, v202
	v_lshlrev_b32_e32 v214, 8, v202
	v_lshl_add_u32 v214, v199, 4, v214
	v_and_b32_e32 v199, 1, v201
	v_lshl_add_u32 v214, v199, 3, v214
	v_add_u32_e32 v214, 0x1e000, v214
	v_and_b32_e32 v200, 1, v163
	v_lshrrev_b32_e32 v199, 1, v201
	v_lshl_add_u32 v199, v200, 3, v199
	v_add_u32_e32 v199, 4, v199
	v_xor_b32_e32 v199, v199, v202
	v_lshlrev_b32_e32 v213, 8, v202
	v_lshl_add_u32 v213, v199, 4, v213
	v_and_b32_e32 v199, 1, v201
	v_lshl_add_u32 v213, v199, 3, v213
	v_add_u32_e32 v213, 0x1e000, v213
	v_and_b32_e32 v200, 1, v163
	v_lshrrev_b32_e32 v199, 1, v201
	v_lshl_add_u32 v199, v200, 3, v199
	v_add_u32_e32 v199, 6, v199
	v_xor_b32_e32 v199, v199, v202
	v_lshlrev_b32_e32 v212, 8, v202
	v_lshl_add_u32 v212, v199, 4, v212
	v_and_b32_e32 v199, 1, v201
	v_lshl_add_u32 v212, v199, 3, v212
	v_add_u32_e32 v212, 0x1e000, v212
	v_bfe_u32 v200, v162, 2, 6
	v_and_b32_e32 v198, 3, v162
	v_lshl_add_u32 v199, v198, 3, 0
	v_lshlrev_b32_e32 v211, 7, v199
	v_bfe_u32 v199, v199, 1, 3
	v_lshrrev_b32_e32 v246, 3, v200
	v_xor_b32_e32 v199, v199, v246
	v_lshl_add_u32 v211, v199, 4, v211
	v_and_b32_e32 v199, 7, v200
	v_lshl_add_u32 v211, v199, 1, v211
	v_add_u32_e32 v211, 0x20100, v211
	v_lshl_add_u32 v199, v198, 3, 1
	v_lshlrev_b32_e32 v210, 7, v199
	v_bfe_u32 v199, v199, 1, 3
	v_lshrrev_b32_e32 v246, 3, v200
	v_xor_b32_e32 v199, v199, v246
	v_lshl_add_u32 v210, v199, 4, v210
	v_and_b32_e32 v199, 7, v200
	v_lshl_add_u32 v210, v199, 1, v210
	v_add_u32_e32 v210, 0x20100, v210
	v_lshl_add_u32 v199, v198, 3, 2
	v_lshlrev_b32_e32 v209, 7, v199
	v_bfe_u32 v199, v199, 1, 3
	v_lshrrev_b32_e32 v246, 3, v200
	v_xor_b32_e32 v199, v199, v246
	v_lshl_add_u32 v209, v199, 4, v209
	v_and_b32_e32 v199, 7, v200
	v_lshl_add_u32 v209, v199, 1, v209
	v_add_u32_e32 v209, 0x20100, v209
	v_lshl_add_u32 v199, v198, 3, 3
	v_lshlrev_b32_e32 v208, 7, v199
	v_bfe_u32 v199, v199, 1, 3
	v_lshrrev_b32_e32 v246, 3, v200
	v_xor_b32_e32 v199, v199, v246
	v_lshl_add_u32 v208, v199, 4, v208
	v_and_b32_e32 v199, 7, v200
	v_lshl_add_u32 v208, v199, 1, v208
	v_add_u32_e32 v208, 0x20100, v208
	v_lshl_add_u32 v199, v198, 3, 4
	v_lshlrev_b32_e32 v207, 7, v199
	v_bfe_u32 v199, v199, 1, 3
	v_lshrrev_b32_e32 v246, 3, v200
	v_xor_b32_e32 v199, v199, v246
	v_lshl_add_u32 v207, v199, 4, v207
	v_and_b32_e32 v199, 7, v200
	v_lshl_add_u32 v207, v199, 1, v207
	v_add_u32_e32 v207, 0x20100, v207
	v_lshl_add_u32 v199, v198, 3, 5
	v_lshlrev_b32_e32 v206, 7, v199
	v_bfe_u32 v199, v199, 1, 3
	v_lshrrev_b32_e32 v246, 3, v200
	v_xor_b32_e32 v199, v199, v246
	v_lshl_add_u32 v206, v199, 4, v206
	v_and_b32_e32 v199, 7, v200
	v_lshl_add_u32 v206, v199, 1, v206
	v_add_u32_e32 v206, 0x20100, v206
	v_lshl_add_u32 v199, v198, 3, 6
	v_lshlrev_b32_e32 v205, 7, v199
	v_bfe_u32 v199, v199, 1, 3
	v_lshrrev_b32_e32 v246, 3, v200
	v_xor_b32_e32 v199, v199, v246
	v_lshl_add_u32 v205, v199, 4, v205
	v_and_b32_e32 v199, 7, v200
	v_lshl_add_u32 v205, v199, 1, v205
	v_add_u32_e32 v205, 0x20100, v205
	v_lshl_add_u32 v199, v198, 3, 7
	v_lshlrev_b32_e32 v204, 7, v199
	v_bfe_u32 v199, v199, 1, 3
	v_lshrrev_b32_e32 v246, 3, v200
	v_xor_b32_e32 v199, v199, v246
	v_lshl_add_u32 v204, v199, 4, v204
	v_and_b32_e32 v199, 7, v200
	v_lshl_add_u32 v204, v199, 1, v204
	v_add_u32_e32 v204, 0x20100, v204
	v_bfe_u32 v200, v162, 2, 6
	v_and_b32_e32 v199, 3, v162
	v_lshlrev_b32_e32 v250, 14, v200
	v_lshl_add_u32 v250, v199, 4, v250
	v_and_b32_e32 v200, 1, v163
	v_lshlrev_b32_e32 v249, 8, v200
	v_lshl_add_u32 v249, v201, 4, v249
	v_lshlrev_b32_e32 v245, 16, v200
	v_lshl_add_u32 v245, v201, 12, v245
	v_lshl_add_u32 v245, v202, 2, v245
	v_add_u32_e32 v244, 0x4000, v245
	v_add_u32_e32 v243, 0x8000, v245
	v_add_u32_e32 v242, 0xc000, v245
	v_lshlrev_b32_e32 v246, 4, v162
	v_add_u32_e32 v246, 0x1e000, v246
	v_mov_b32_e32 v8, 0
	v_mov_b32_e32 v9, 0
	v_mov_b32_e32 v10, 0
	v_mov_b32_e32 v11, 0
	s_cmp_gt_u32 s32, 3
	s_cbranch_scc1 .Lp3V_entry
	s_cmp_gt_u32 s32, 1
	s_cbranch_scc1 .Lp3S_entry

.Lp3O_item:
	s_cmp_eq_u32 s49, 1
	s_cbranch_scc1 .Lp3O_have
	s_lshr_b32 s4, s3, 3
	s_and_b32 s41, s4, 7
	s_lshr_b32 s5, s4, 3
	s_and_b32 s37, s3, 7
	s_lshl_b32 s37, s37, 2
	s_add_i32 s37, s37, s5
	s_lshr_b32 s39, s37, 2
	s_and_b32 s40, s37, 3
	s_add_u32 s8, s94, 0x1d800000
	s_addc_u32 s9, s95, 0
	s_lshl_b32 s31, s39, 21
	s_add_u32 s8, s8, s31
	s_addc_u32 s9, s9, 0
	s_lshl_b32 s31, s40, 8
	s_add_u32 s8, s8, s31
	s_addc_u32 s9, s9, 0
	s_add_u32 s10, s94, 0x2f00000
	s_addc_u32 s11, s95, 0
	s_lshl_b32 s31, s37, 18
	s_add_u32 s10, s10, s31
	s_addc_u32 s11, s11, 0
	s_add_u32 s12, s94, 0x3700000
	s_addc_u32 s13, s95, 0
	s_lshl_b32 s31, s37, 19
	s_add_u32 s12, s12, s31
	s_addc_u32 s13, s13, 0
	s_mov_b32 m0, s46
	s_nop 0
	global_load_lds_dwordx4 v255, s[8:9]
	s_add_i32 m0, s46, 0x400
	s_nop 0
	global_load_lds_dwordx4 v254, s[8:9]
	s_mov_b32 m0, s47
	s_nop 0
	global_load_lds_dwordx4 v253, s[10:11]
	s_mov_b32 m0, s48
	s_nop 0
	global_load_lds_dwordx4 v252, s[12:13]
	s_add_i32 m0, s48, 0x400
	s_nop 0
	global_load_lds_dwordx4 v251, s[12:13]
	s_add_u32 s8, s8, 0x10000
	s_addc_u32 s9, s9, 0
	s_add_u32 s10, s10, 0x2000
	s_addc_u32 s11, s11, 0
	s_add_u32 s12, s12, 0x4000
	s_addc_u32 s13, s13, 0
	s_add_i32 m0, s46, 0xa000
	s_nop 0
	global_load_lds_dwordx4 v255, s[8:9]
	s_add_i32 m0, s46, 0xa400
	s_nop 0
	global_load_lds_dwordx4 v254, s[8:9]
	s_add_i32 m0, s47, 0xa000
	s_nop 0
	global_load_lds_dwordx4 v253, s[10:11]
	s_add_i32 m0, s48, 0xa000
	s_nop 0
	global_load_lds_dwordx4 v252, s[12:13]
	s_add_i32 m0, s48, 0xa400
	s_nop 0
	global_load_lds_dwordx4 v251, s[12:13]
	s_add_u32 s8, s8, 0x10000
	s_addc_u32 s9, s9, 0
	s_add_u32 s10, s10, 0x2000
	s_addc_u32 s11, s11, 0
	s_add_u32 s12, s12, 0x4000
	s_addc_u32 s13, s13, 0
.Lp3O_have:
	s_mov_b32 s49, 0
	s_add_u32 s18, s6, 0x0
	s_addc_u32 s19, s7, 0
	s_lshl_b32 s31, s39, 22
	s_add_u32 s18, s18, s31
	s_addc_u32 s19, s19, 0
	s_lshl_b32 s31, s40, 9
	s_add_u32 s18, s18, s31
	s_addc_u32 s19, s19, 0
	s_lshl_b32 s31, s41, 6
	s_add_u32 s18, s18, s31
	s_addc_u32 s19, s19, 0
	ds_write_b128 v246, v[8:11]
	s_waitcnt vmcnt(0)
	s_mov_b32 s33, 0
	s_waitcnt lgkmcnt(0)
	s_barrier

; #define LAS __attribute__((address_space(3)))
; __device__ __forceinline__ void gla_scan_item(const Ctx& C, int item, LAS unsigned char* lds, int tid) {
;     ...
;     f32x4 S[2] = {(f32x4){0.f, 0.f, 0.f, 0.f}, (f32x4){0.f, 0.f, 0.f, 0.f}};
;     *(LAS u32x4*)(Bc + (tid >> 4) * 200 + (tid & 15) * 8) = (u32x4){0u, 0u, 0u, 0u};
;     u32x4 rq0A, rq1A, rsA, rk0A, rk1A, rvA = (u32x4){0u, 0u, 0u, 0u}; f32x4 rdA;
;     u32x4 rq0B, rq1B, rsB, rk0B, rk1B, rvB = (u32x4){0u, 0u, 0u, 0u}; f32x4 rdB;
.Lp3S_have:
	s_mov_b32 s49, 0
	s_add_u32 s16, s94, 0x2e00000
	s_addc_u32 s17, s95, 0
	s_lshl_b32 s31, s37, 14
	s_add_u32 s16, s16, s31
	s_addc_u32 s17, s17, 0
	s_add_u32 s34, s92, 0x4090000
	s_addc_u32 s35, s93, 0
	s_lshl_b32 s31, s37, 17
	s_add_u32 s34, s34, s31
	s_addc_u32 s35, s35, 0
	s_lshl_b32 s31, s41, 7
	s_add_u32 s34, s34, s31
	s_addc_u32 s35, s35, 0
	v_mov_b32_e32 v60, 0
	v_mov_b32_e32 v61, 0
	v_mov_b32_e32 v62, 0
	v_mov_b32_e32 v63, 0
	v_mov_b32_e32 v64, 0
	v_mov_b32_e32 v65, 0
	v_mov_b32_e32 v66, 0
	v_mov_b32_e32 v67, 0
	v_mov_b32_e32 v68, 0
	v_mov_b32_e32 v69, 0
	v_mov_b32_e32 v70, 0
	v_mov_b32_e32 v71, 0
	v_mov_b32_e32 v72, 0
	v_mov_b32_e32 v73, 0
	v_mov_b32_e32 v74, 0
	v_mov_b32_e32 v75, 0
	v_mov_b32_e32 v76, 0
	v_mov_b32_e32 v77, 0
	v_mov_b32_e32 v78, 0
	v_mov_b32_e32 v79, 0
	v_mov_b32_e32 v80, 0
	v_mov_b32_e32 v81, 0
	v_mov_b32_e32 v82, 0
	v_mov_b32_e32 v83, 0
	v_mov_b32_e32 v84, 0
	v_mov_b32_e32 v85, 0
	v_mov_b32_e32 v86, 0
	v_mov_b32_e32 v87, 0
	v_mov_b32_e32 v88, 0
	v_mov_b32_e32 v89, 0
	v_mov_b32_e32 v90, 0
	v_mov_b32_e32 v91, 0
	ds_write_b128 v246, v[8:11]
	global_load_dwordx4 v[92:95], v249, s[16:17] offset:0
	global_load_dwordx4 v[96:99], v249, s[16:17] offset:64
	global_load_dwordx4 v[100:103], v249, s[16:17] offset:128
	global_load_dwordx4 v[104:107], v249, s[16:17] offset:192
	s_add_u32 s16, s16, 0x200
	s_addc_u32 s17, s17, 0
	global_load_dwordx4 v[108:111], v249, s[16:17] offset:0
	global_load_dwordx4 v[112:115], v249, s[16:17] offset:64
	global_load_dwordx4 v[116:119], v249, s[16:17] offset:128
	global_load_dwordx4 v[120:123], v249, s[16:17] offset:192
	s_add_u32 s16, s16, 0x200
	s_addc_u32 s17, s17, 0
	global_load_dwordx4 v[124:127], v249, s[16:17] offset:0
	global_load_dwordx4 v[128:131], v249, s[16:17] offset:64
	global_load_dwordx4 v[132:135], v249, s[16:17] offset:128
	global_load_dwordx4 v[136:139], v249, s[16:17] offset:192
	s_add_u32 s16, s16, 0x200
	s_addc_u32 s17, s17, 0
	s_waitcnt vmcnt(0)
	s_mov_b32 s33, 0
	s_waitcnt lgkmcnt(0)
	s_barrier

.Lp3V_have:
	s_mov_b32 s49, 0
	s_add_u32 s14, s94, 0xd402000
	s_addc_u32 s15, s95, 0
	s_lshl_b32 s31, s39, 25
	s_add_u32 s14, s14, s31
	s_addc_u32 s15, s15, 0
	s_lshl_b32 s31, s40, 9
	s_add_u32 s14, s14, s31
	s_addc_u32 s15, s15, 0
	s_lshl_b32 s31, s41, 6
	s_add_u32 s14, s14, s31
	s_addc_u32 s15, s15, 0
	ds_write_b128 v246, v[8:11]
	global_load_dwordx4 v[12:15], v250, s[14:15]
	s_add_u32 s14, s14, 0x100000
	s_addc_u32 s15, s15, 0
	global_load_dwordx4 v[16:19], v250, s[14:15]
	s_add_u32 s14, s14, 0x100000
	s_addc_u32 s15, s15, 0
	global_load_dwordx4 v[20:23], v250, s[14:15]
	s_add_u32 s14, s14, 0x100000
	s_addc_u32 s15, s15, 0
	s_waitcnt vmcnt(0)
	ds_write_b16 v211, v12 offset:0
	ds_write_b16_d16_hi v210, v12 offset:0
	ds_write_b16 v209, v13 offset:0
	ds_write_b16_d16_hi v208, v13 offset:0
	ds_write_b16 v207, v14 offset:0
	ds_write_b16_d16_hi v206, v14 offset:0
	ds_write_b16 v205, v15 offset:0
	ds_write_b16_d16_hi v204, v15 offset:0
	s_mov_b32 s33, 0
	s_waitcnt lgkmcnt(0)
	s_barrier
